# scan-v6-bonus-to-step3
# speedup vs baseline: 1.0324x; 1.0109x over previous
.LBB0_568:
	s_or_b64 exec, exec, s[22:23]
	v_mov_b32_e32 v3, v0
	s_mov_b64 s[22:23], -1
	v_and_b32_e32 v88, 15, v3
	s_waitcnt vmcnt(5)
	v_bfe_u32 v2, v3, 4, 2
	v_or_b32_e32 v4, s82, v88
	ds_read_b64_tr_b16 v[66:67], v241
	ds_read_b64_tr_b16 v[68:69], v241 offset:1024
	ds_read_b64_tr_b16 v[74:75], v241 offset:32768
	ds_read_b64_tr_b16 v[76:77], v241 offset:33792
	ds_read_b64_tr_b16 v[70:71], v241 offset:2048
	ds_read_b64_tr_b16 v[72:73], v241 offset:3072
	ds_read_b64_tr_b16 v[78:79], v241 offset:34816
	ds_read_b64_tr_b16 v[80:81], v241 offset:35840
	v_lshlrev_b32_e32 v92, 2, v2
	s_and_b64 vcc, exec, s[4:5]
	v_lshlrev_b32_e32 v86, 5, v4
	v_lshlrev_b32_e32 v87, 3, v2
	v_cmp_lt_u32_e64 s[18:19], v92, v88
	v_or_b32_e32 v91, 1, v92
	v_or_b32_e32 v90, 2, v92
	v_or_b32_e32 v89, 3, v92
	s_cbranch_vccz .LBB0_576
	ds_read_b64_tr_b16 v[94:95], v241 offset:8
	ds_read_b64_tr_b16 v[96:97], v241 offset:1032
	ds_read_b64_tr_b16 v[106:107], v241 offset:32776
	ds_read_b64_tr_b16 v[108:109], v241 offset:33800
	ds_read_b64_tr_b16 v[98:99], v241 offset:2056
	ds_read_b64_tr_b16 v[100:101], v241 offset:3080
	s_waitcnt lgkmcnt(4)
	v_mfma_f32_16x16x32_bf16 v[102:105], v[74:77], v[94:97], 0
	ds_read_b64_tr_b16 v[82:83], v241 offset:34824
	ds_read_b64_tr_b16 v[84:85], v241 offset:35848
	v_cmp_gt_u32_e64 s[24:25], v90, v88
	v_mov_b32_e32 v118, s67
	v_mov_b32_e32 v120, s67
	s_waitcnt lgkmcnt(4)
	v_mfma_f32_16x16x32_bf16 v[114:117], v[106:109], v[94:97], 0
	v_cmp_gt_u32_e32 vcc, v92, v88
	v_cmp_lt_u32_e64 s[22:23], v90, v88
	v_lshlrev_b32_e32 v4, 6, v4
	v_mfma_f32_16x16x32_bf16 v[110:113], v[106:109], v[66:69], 0
	v_lshlrev_b32_e32 v122, 16, v94
	v_and_b32_e32 v123, 0xffff0000, v94
	v_and_b32_e32 v3, 3, v3
	s_waitcnt lgkmcnt(2)
	v_mfma_f32_16x16x32_bf16 v[102:105], v[78:81], v[98:101], v[102:105]
	s_waitcnt lgkmcnt(0)
	v_mfma_f32_16x16x32_bf16 v[114:117], v[82:85], v[98:101], v[114:117]
	v_mfma_f32_16x16x32_bf16 v[110:113], v[82:85], v[70:73], v[110:113]
	s_nop 4
	v_cndmask_b32_e64 v104, v104, 0, s[24:25]
	s_nop 0
	v_cndmask_b32_e64 v116, v116, 0, s[24:25]
	v_cmp_lt_u32_e64 s[24:25], v89, v88
	v_cndmask_b32_e32 v93, v114, v120, vcc
	v_cndmask_b32_e32 v118, v102, v118, vcc
	v_cmp_lt_u32_e32 vcc, v91, v88
	s_or_b64 s[22:23], s[24:25], s[22:23]
	s_or_b64 vcc, s[22:23], vcc
	v_cndmask_b32_e64 v93, v93, v114, s[18:19]
	v_cndmask_b32_e64 v114, 0, v115, s[18:19]
	v_cndmask_b32_e64 v115, v118, v102, s[18:19]
	v_cndmask_b32_e32 v102, 0, v111, vcc
	s_or_b64 vcc, vcc, s[18:19]
	v_cndmask_b32_e64 v118, 0, v103, s[18:19]
	v_cndmask_b32_e64 v103, 0, v113, s[24:25]
	v_cndmask_b32_e64 v112, 0, v112, s[22:23]
	v_cndmask_b32_e32 v110, 0, v110, vcc
	v_cmp_gt_u32_e32 vcc, v89, v88
	v_cvt_pk_bf16_f32 v102, v110, v102
	v_cvt_pk_bf16_f32 v103, v112, v103
	v_cndmask_b32_e64 v105, v105, 0, vcc
	v_add3_u32 v110, s72, v86, v87
	v_cndmask_b32_e64 v111, v117, 0, vcc
	ds_write_b64 v110, v[102:103]
	v_cvt_pk_bf16_f32 v103, v104, v105
	v_cvt_pk_bf16_f32 v104, v93, v114
	v_lshlrev_b32_e32 v93, 4, v2
	v_cvt_pk_bf16_f32 v102, v115, v118
	v_cvt_pk_bf16_f32 v105, v116, v111
	v_add3_u32 v4, s71, v4, v93
	ds_write_b128 v4, v[102:105]
	s_mov_b64 s[22:23], 0

.LBB0_578:
	s_mov_b64 s[18:19], -1
	s_and_b64 vcc, exec, s[4:5]
	s_waitcnt lgkmcnt(0)
	s_barrier
	s_cbranch_vccz .LBB0_606
	v_lshl_add_u32 v4, v2, 5, 0
	ds_read_b128 v[102:105], v4 offset:22016
	ds_read_b128 v[110:113], v4 offset:22032
	ds_read_b128 v[114:117], v4 offset:22144
	ds_read_b128 v[118:121], v4 offset:22160
	v_cmp_lt_i32_e32 vcc, 0, v3
	s_waitcnt lgkmcnt(3)
	v_pk_mul_f32 v[102:103], v[102:103], v[122:123]
	s_nop 0
	v_cvt_pk_bf16_f32 v94, v102, v103
	v_lshlrev_b32_e32 v102, 16, v98
	v_and_b32_e32 v103, 0xffff0000, v98
	s_waitcnt lgkmcnt(1)
	v_pk_mul_f32 v[102:103], v[114:115], v[102:103]
	s_nop 0
	v_cvt_pk_bf16_f32 v98, v102, v103
	v_lshlrev_b32_e32 v102, 16, v95
	v_and_b32_e32 v103, 0xffff0000, v95
	v_pk_mul_f32 v[102:103], v[104:105], v[102:103]
	s_nop 0
	v_cvt_pk_bf16_f32 v95, v102, v103
	v_lshlrev_b32_e32 v102, 16, v99
	v_and_b32_e32 v103, 0xffff0000, v99
	v_pk_mul_f32 v[102:103], v[116:117], v[102:103]
	s_nop 0
	v_cvt_pk_bf16_f32 v99, v102, v103
	v_lshlrev_b32_e32 v102, 16, v96
	v_and_b32_e32 v103, 0xffff0000, v96
	v_pk_mul_f32 v[102:103], v[110:111], v[102:103]
	s_nop 0
	v_cvt_pk_bf16_f32 v96, v102, v103
	v_lshlrev_b32_e32 v102, 16, v100
	v_and_b32_e32 v103, 0xffff0000, v100
	s_waitcnt lgkmcnt(0)
	v_pk_mul_f32 v[102:103], v[118:119], v[102:103]
	s_nop 0
	v_cvt_pk_bf16_f32 v100, v102, v103
	v_lshlrev_b32_e32 v102, 16, v97
	v_and_b32_e32 v103, 0xffff0000, v97
	v_pk_mul_f32 v[102:103], v[112:113], v[102:103]
	s_nop 0
	v_cvt_pk_bf16_f32 v97, v102, v103
	v_lshlrev_b32_e32 v102, 16, v101
	v_and_b32_e32 v103, 0xffff0000, v101
	v_mfma_f32_16x16x32_bf16 v[94:97], v[106:109], v[94:97], 0
	v_mul_f32_e64 v102, v120, v102
	v_mul_f32_e64 v103, v121, v103
	v_cvt_pk_bf16_f32 v101, v102, v103
	s_nop 1
	v_mfma_f32_16x16x32_bf16 v[82:85], v[82:85], v[98:101], v[94:97]
	s_and_saveexec_b64 s[18:19], vcc
	s_xor_b64 s[18:19], exec, s[18:19]
	s_cbranch_execz .LBB0_573
	v_cmp_ne_u32_e32 vcc, 1, v3
	s_nop 3
	v_mov_b32_e32 v82, v83
	s_and_saveexec_b64 s[22:23], vcc
	s_xor_b64 s[22:23], exec, s[22:23]
	v_cmp_eq_u32_e32 vcc, 2, v3
	s_nop 1
	v_cndmask_b32_e32 v82, v85, v84, vcc
	s_andn2_saveexec_b64 s[22:23], s[22:23]
	s_or_b64 exec, exec, s[22:23]
.LBB0_573:
	s_andn2_saveexec_b64 s[18:19], s[18:19]
	s_or_b64 exec, exec, s[18:19]
	v_lshrrev_b32_e32 v3, 2, v88
	v_cmp_eq_u32_e32 vcc, v2, v3
	s_and_saveexec_b64 s[18:19], vcc
	s_and_b32 s22, s30, 64
	s_lshl_b32 s22, s22, 2
	s_add_i32 s22, s83, s22
	v_lshl_add_u32 v2, v88, 2, s22
	ds_write_b32 v2, v82 offset:20480
	s_or_b64 exec, exec, s[18:19]
	s_andn2_b64 vcc, exec, s[48:49]
	s_cbranch_vccnz .LBB0_605
	s_cmp_eq_u32 s51, 30
	v_mov_b32_e32 v2, v0
	s_cselect_b64 s[18:19], -1, 0
	s_and_b64 s[22:23], s[16:17], s[18:19]
	v_and_b32_e32 v66, 63, v2
	s_and_b64 s[18:19], s[16:17], exec
	v_and_b32_e32 v68, 7, v2
	v_or_b32_e32 v2, s69, v66
	s_cselect_b32 s2, s2, s81
	v_lshrrev_b32_e32 v3, 3, v2
	s_cmpk_eq_i32 s2, 0x7c0
	v_sub_u32_e32 v4, 0x41, v3
	v_cmp_gt_u32_e32 vcc, 8, v2
	s_cselect_b64 s[18:19], -1, 0
	v_cndmask_b32_e64 v3, v3, v4, s[16:17]
	s_and_b64 s[24:25], s[22:23], vcc
	v_lshlrev_b32_e32 v67, 5, v68
	v_cndmask_b32_e64 v2, v65, 0, s[24:25]
	v_cndmask_b32_e64 v65, v63, 0, s[24:25]
	v_cndmask_b32_e64 v63, v62, 0, s[24:25]
	v_mul_u32_u24_e32 v3, 0x110, v3
	v_cndmask_b32_e64 v4, v64, 0, s[24:25]
	v_add3_u32 v3, 0, v3, v67
	v_lshlrev_b32_e32 v62, 16, v63
	v_and_b32_e32 v63, 0xffff0000, v63
	v_lshlrev_b32_e32 v64, 16, v65
	v_and_b32_e32 v65, 0xffff0000, v65
	ds_write_b128 v3, v[62:65] offset:22528
	v_lshlrev_b32_e32 v64, 16, v2
	v_and_b32_e32 v65, 0xffff0000, v2
	v_or_b32_e32 v2, s73, v66
	v_lshlrev_b32_e32 v62, 16, v4
	v_and_b32_e32 v63, 0xffff0000, v4
	v_lshrrev_b32_e32 v2, 3, v2
	ds_write_b128 v3, v[62:65] offset:22544
	v_sub_u32_e32 v3, 0x41, v2
	v_cndmask_b32_e64 v2, v2, v3, s[16:17]
	v_mul_u32_u24_e32 v2, 0x110, v2
	v_add3_u32 v2, 0, v2, v67
	v_lshlrev_b32_e32 v62, 16, v58
	v_and_b32_e32 v63, 0xffff0000, v58
	v_lshlrev_b32_e32 v64, 16, v59
	v_and_b32_e32 v65, 0xffff0000, v59
	v_lshlrev_b32_e32 v58, 16, v60
	v_and_b32_e32 v59, 0xffff0000, v60
	v_lshlrev_b32_e32 v60, 16, v61
	v_and_b32_e32 v61, 0xffff0000, v61
	ds_write_b128 v2, v[58:61] offset:22544
	v_or_b32_e32 v58, s74, v66
	ds_write_b128 v2, v[62:65] offset:22528
	v_mul_hi_u32_u24_e32 v2, 0x7c1f08, v58
	v_mul_u32_u24_e32 v2, 0x210, v2
	v_sub_u32_e32 v59, v58, v2
	v_cmp_gt_u32_e32 vcc, 8, v59
	s_and_b64 s[24:25], s[22:23], vcc
	s_xor_b64 vcc, s[24:25], -1
	s_and_saveexec_b64 s[48:49], vcc
	v_and_b32_e32 v2, 0x3f8, v59
	v_cmp_eq_u32_e32 vcc, s65, v2
	s_and_b64 vcc, s[18:19], vcc
	s_andn2_b64 s[24:25], s[24:25], exec
	s_and_b64 vcc, vcc, exec
	s_or_b64 s[24:25], s[24:25], vcc
	s_or_b64 exec, exec, s[48:49]
	s_and_saveexec_b64 s[48:49], s[24:25]
	v_mov_b32_e32 v4, v5
	v_mov_b32_e32 v2, v5
	v_mov_b32_e32 v3, v5
	v_mov_b64_e32 v[56:57], v[4:5]
	v_mov_b64_e32 v[54:55], v[2:3]
	s_or_b64 exec, exec, s[48:49]
	v_lshrrev_b32_e32 v2, 3, v59
	s_movk_i32 s2, 0x210
	v_sub_u32_e32 v3, 0x41, v2
	v_cmp_gt_u32_e32 vcc, s2, v58
	v_cndmask_b32_e64 v2, v2, v3, s[16:17]
	v_mul_u32_u24_e32 v2, 0x110, v2
	v_cndmask_b32_e32 v3, v198, v199, vcc
	v_add_u32_e32 v3, 0, v3
	v_add3_u32 v2, v3, v2, v67
	v_lshlrev_b32_e32 v58, 16, v54
	v_and_b32_e32 v59, 0xffff0000, v54
	v_lshlrev_b32_e32 v60, 16, v55
	v_and_b32_e32 v61, 0xffff0000, v55
	v_lshlrev_b32_e32 v54, 16, v56
	v_and_b32_e32 v55, 0xffff0000, v56
	v_lshlrev_b32_e32 v56, 16, v57
	v_and_b32_e32 v57, 0xffff0000, v57
	ds_write_b128 v2, v[58:61]
	ds_write_b128 v2, v[54:57] offset:16
	v_or_b32_e32 v2, s75, v66
	v_mul_hi_u32_u24_e32 v3, 0x7c1f08, v2
	v_mul_u32_u24_e32 v3, 0x210, v3
	v_sub_u32_e32 v54, v2, v3
	v_cmp_gt_u32_e32 vcc, 8, v54
	s_and_b64 s[24:25], s[22:23], vcc
	s_xor_b64 vcc, s[24:25], -1
	s_and_saveexec_b64 s[48:49], vcc
	v_and_b32_e32 v2, 0x3f8, v54
	v_cmp_eq_u32_e32 vcc, s65, v2
	s_and_b64 vcc, s[18:19], vcc
	s_andn2_b64 s[24:25], s[24:25], exec
	s_and_b64 vcc, vcc, exec
	s_or_b64 s[24:25], s[24:25], vcc
	s_or_b64 exec, exec, s[48:49]
	s_and_saveexec_b64 s[48:49], s[24:25]
	v_mov_b32_e32 v4, v5
	v_mov_b32_e32 v2, v5
	v_mov_b32_e32 v3, v5
	v_mov_b64_e32 v[52:53], v[4:5]
	v_mov_b64_e32 v[50:51], v[2:3]
	s_or_b64 exec, exec, s[48:49]
	v_lshrrev_b32_e32 v2, 3, v54
	v_sub_u32_e32 v3, 0x41, v2
	v_cndmask_b32_e64 v2, v2, v3, s[16:17]
	v_mul_u32_u24_e32 v2, 0x110, v2
	v_add3_u32 v2, 0, v2, v67
	v_lshlrev_b32_e32 v54, 16, v50
	v_and_b32_e32 v55, 0xffff0000, v50
	v_lshlrev_b32_e32 v56, 16, v51
	v_and_b32_e32 v57, 0xffff0000, v51
	v_lshlrev_b32_e32 v50, 16, v52
	v_and_b32_e32 v51, 0xffff0000, v52
	v_lshlrev_b32_e32 v52, 16, v53
	v_and_b32_e32 v53, 0xffff0000, v53
	ds_write_b128 v2, v[50:53] offset:40496
	v_or_b32_e32 v51, s76, v66
	ds_write_b128 v2, v[54:57] offset:40480
	v_mul_hi_u32_u24_e32 v2, 0x7c1f08, v51
	v_mul_u32_u24_e32 v2, 0x210, v2
	v_sub_u32_e32 v50, v51, v2
	v_cmp_gt_u32_e32 vcc, 8, v50
	s_and_b64 s[24:25], s[22:23], vcc
	s_xor_b64 vcc, s[24:25], -1
	s_and_saveexec_b64 s[48:49], vcc
	v_and_b32_e32 v2, 0x3f8, v50
	v_cmp_eq_u32_e32 vcc, s65, v2
	s_and_b64 vcc, s[18:19], vcc
	s_andn2_b64 s[24:25], s[24:25], exec
	s_and_b64 vcc, vcc, exec
	s_or_b64 s[24:25], s[24:25], vcc
	s_or_b64 exec, exec, s[48:49]
	s_and_saveexec_b64 s[48:49], s[24:25]
	v_mov_b32_e32 v4, v5
	v_mov_b32_e32 v2, v5
	v_mov_b32_e32 v3, v5
	v_mov_b64_e32 v[48:49], v[4:5]
	v_mov_b64_e32 v[46:47], v[2:3]
	s_or_b64 exec, exec, s[48:49]
	v_lshrrev_b32_e32 v2, 3, v50
	v_sub_u32_e32 v3, 0x41, v2
	v_cndmask_b32_e64 v2, v2, v3, s[16:17]
	v_lshl_add_u32 v50, v68, 4, 0
	v_cmp_lt_u32_e32 vcc, s34, v51
	s_and_saveexec_b64 s[24:25], vcc
	s_xor_b64 s[24:25], exec, s[24:25]
	v_lshl_add_u32 v2, v2, 7, v50
	ds_write_b128 v2, v[46:49] offset:58432
	s_andn2_saveexec_b64 s[24:25], s[24:25]
	s_cbranch_execz .LBB0_596
	v_mul_u32_u24_e32 v2, 0x110, v2
	v_add3_u32 v2, 0, v2, v67
	v_lshlrev_b32_e32 v52, 16, v46
	v_and_b32_e32 v53, 0xffff0000, v46
	v_lshlrev_b32_e32 v54, 16, v47
	v_and_b32_e32 v55, 0xffff0000, v47
	v_lshlrev_b32_e32 v46, 16, v48
	v_and_b32_e32 v47, 0xffff0000, v48
	v_lshlrev_b32_e32 v48, 16, v49
	v_and_b32_e32 v49, 0xffff0000, v49
	ds_write_b128 v2, v[52:55] offset:40480
	ds_write_b128 v2, v[46:49] offset:40496
